# in-proj GEMM main-loop head pinned to a 64-byte boundary (byte-phase placement trial)
# baseline (speedup 1.0000x reference)
;     __device__ __forceinline__ bool next(int i, Unit& u) const { return static_next((long)i * G + c, nM, nN, u); }
;     __device__ __forceinline__ const char* aptr(const Unit& u) const { return (const char*)(A + (size_t)u.pm * 256 * K); }
;     __device__ __forceinline__ const char* bptr(const Unit& u) const { return (const char*)(B + (size_t)u.pn * 256 * K); }
;     __device__ __forceinline__ bool next(int i, Unit& u) const { if (i > 0 || c >= 32) return false; u.z = c >> 4; u.pm = c & 15; u.pn = 0; return true; }
;     __device__ __forceinline__ const char* aptr(const Unit& u) const { return (const char*)(A0 + ((size_t)u.z * 4096 + (size_t)u.pm * 256) * 2048); }
;     __device__ __forceinline__ const char* bptr(const Unit& u) const { return (const char*)(W1T + (size_t)u.z * 256 * 2048); }
;     __device__ __forceinline__ bool next(int i, Unit& u) const { const bool ok = static_next((long)(i >> 2) * G + c, 64, 8, u); u.z = i & 3; return ok; }
;     __device__ __forceinline__ const char* aptr(const Unit& u) const { return (const char*)(O + ((size_t)u.z * MT + (size_t)u.pm * 256) * DBR); }
;     __device__ __forceinline__ const char* bptr(const Unit& u) const { return (const char*)(WBR + ((size_t)u.z * DM + (size_t)u.pn * 256) * DBR); }
;     __device__ __forceinline__ bool next(int i, Unit& u) const { if (i > 1) return false; const int x = c & 7, k = c >> 3; u.pm = 32 * i + 4 * x + (k >> 3); u.pn = k & 7; u.z = 0; return true; }
; template <class Epi, class Sched>
; __device__ __forceinline__ void gemm_phase(LAS unsigned char* lds, const int K, const Sched& S, const Epi& E) {
;     ...
;         const bool has_next = S.next(ui + 1, nxt);
;         const char* nA = has_next ? S.aptr(nxt) : cA; const char* nB = has_next ? S.bptr(nxt) : cB;
;         for (int t = 0; t < nt; t += 2) {
;             const bool last = (t == nt - 2);
;             const char* a1 = cA + (size_t)(t + 1) * kstep;
;             const char* a2 = last ? nA : cA + (size_t)(t + 2) * kstep; const char* b2 = last ? nB : cB + (size_t)(t + 2) * kstep;
;             const char* a3 = a2 + kstep; const char* b3 = b2 + kstep;
;             PG8_LDB(B0, 0, 0); PG8_LDB(B1, 0, 1); PG8_SCHED; PG8_LDA(At, 0, 0); PG8_STAGE(PG8_SA(1, 1), a1 + hstep, voffA);
;             PG8_WAIT_V(8); PG8_WAIT_L(0); PG8_BAR; PG8_MMA(0, 0, At, B0); PG8_MMA(0, 1, At, B1); PG8_BAR; PG8_SCHED;
.LBB0_919:
	s_ashr_i32 s17, s16, 31
	s_lshl_b64 s[18:19], s[16:17], 20
	s_add_u32 s18, s26, s18
	s_addc_u32 s19, s27, s19
	s_and_b64 s[20:21], s[6:7], exec
	s_cselect_b32 s17, s19, s5
	s_cselect_b32 s71, s18, s4
	s_ashr_i32 s15, s14, 31
	s_lshl_b64 s[20:21], s[14:15], 20
	s_add_u32 s20, s28, s20
	s_addc_u32 s21, s29, s21
	s_and_b64 s[24:25], s[6:7], exec
	s_cselect_b32 s15, s21, s9
	s_cselect_b32 s76, s20, s8
	s_add_u32 s4, s4, 0x80080
	s_addc_u32 s5, s5, 0
	s_add_u32 s77, s8, 0x100
	v_mov_b32_e32 v2, 0
	s_addc_u32 s82, s9, 0
	s_mov_b32 s83, -2
	v_mov_b32_e32 v3, v2
	v_mov_b32_e32 v4, v2
	v_mov_b32_e32 v5, v2
	v_mov_b32_e32 v6, v2
	v_mov_b32_e32 v7, v2
	v_mov_b32_e32 v8, v2
	v_mov_b32_e32 v9, v2
	v_mov_b32_e32 v18, v2
	v_mov_b32_e32 v19, v2
	v_mov_b32_e32 v20, v2
	v_mov_b32_e32 v21, v2
	v_mov_b32_e32 v22, v2
	v_mov_b32_e32 v23, v2
	v_mov_b32_e32 v24, v2
	v_mov_b32_e32 v25, v2
	v_mov_b32_e32 v34, v2
	v_mov_b32_e32 v35, v2
	v_mov_b32_e32 v36, v2
	v_mov_b32_e32 v37, v2
	v_mov_b32_e32 v38, v2
	v_mov_b32_e32 v39, v2
	v_mov_b32_e32 v40, v2
	v_mov_b32_e32 v41, v2
	v_mov_b32_e32 v50, v2
	v_mov_b32_e32 v51, v2
	v_mov_b32_e32 v52, v2
	v_mov_b32_e32 v53, v2
	v_mov_b32_e32 v54, v2
	v_mov_b32_e32 v55, v2
	v_mov_b32_e32 v56, v2
	v_mov_b32_e32 v57, v2
	v_mov_b32_e32 v10, v2
	v_mov_b32_e32 v11, v2
	v_mov_b32_e32 v12, v2
	v_mov_b32_e32 v13, v2
	v_mov_b32_e32 v14, v2
	v_mov_b32_e32 v15, v2
	v_mov_b32_e32 v16, v2
	v_mov_b32_e32 v17, v2
	v_mov_b32_e32 v26, v2
	v_mov_b32_e32 v27, v2
	v_mov_b32_e32 v28, v2
	v_mov_b32_e32 v29, v2
	v_mov_b32_e32 v30, v2
	v_mov_b32_e32 v31, v2
	v_mov_b32_e32 v32, v2
	v_mov_b32_e32 v33, v2
	v_mov_b32_e32 v42, v2
	v_mov_b32_e32 v43, v2
	v_mov_b32_e32 v44, v2
	v_mov_b32_e32 v45, v2
	v_mov_b32_e32 v46, v2
	v_mov_b32_e32 v47, v2
	v_mov_b32_e32 v48, v2
	v_mov_b32_e32 v49, v2
	v_mov_b32_e32 v58, v2
	v_mov_b32_e32 v59, v2
	v_mov_b32_e32 v60, v2
	v_mov_b32_e32 v61, v2
	v_mov_b32_e32 v62, v2
	v_mov_b32_e32 v63, v2
	v_mov_b32_e32 v64, v2
	v_mov_b32_e32 v65, v2
	v_mov_b32_e32 v66, v2
	v_mov_b32_e32 v67, v2
	v_mov_b32_e32 v68, v2
	v_mov_b32_e32 v69, v2
	v_mov_b32_e32 v70, v2
	v_mov_b32_e32 v71, v2
	v_mov_b32_e32 v72, v2
	v_mov_b32_e32 v73, v2
	v_mov_b32_e32 v82, v2
	v_mov_b32_e32 v83, v2
	v_mov_b32_e32 v84, v2
	v_mov_b32_e32 v85, v2
	v_mov_b32_e32 v86, v2
	v_mov_b32_e32 v87, v2
	v_mov_b32_e32 v88, v2
	v_mov_b32_e32 v89, v2
	v_mov_b32_e32 v98, v2
	v_mov_b32_e32 v99, v2
	v_mov_b32_e32 v100, v2
	v_mov_b32_e32 v101, v2
	v_mov_b32_e32 v102, v2
	v_mov_b32_e32 v103, v2
	v_mov_b32_e32 v104, v2
	v_mov_b32_e32 v105, v2
	v_mov_b32_e32 v114, v2
	v_mov_b32_e32 v115, v2
	v_mov_b32_e32 v116, v2
	v_mov_b32_e32 v117, v2
	v_mov_b32_e32 v118, v2
	v_mov_b32_e32 v119, v2
	v_mov_b32_e32 v120, v2
	v_mov_b32_e32 v121, v2
	v_mov_b32_e32 v74, v2
	v_mov_b32_e32 v75, v2
	v_mov_b32_e32 v76, v2
	v_mov_b32_e32 v77, v2
	v_mov_b32_e32 v78, v2
	v_mov_b32_e32 v79, v2
	v_mov_b32_e32 v80, v2
	v_mov_b32_e32 v81, v2
	v_mov_b32_e32 v90, v2
	v_mov_b32_e32 v91, v2
	v_mov_b32_e32 v92, v2
	v_mov_b32_e32 v93, v2
	v_mov_b32_e32 v94, v2
	v_mov_b32_e32 v95, v2
	v_mov_b32_e32 v96, v2
	v_mov_b32_e32 v97, v2
	v_mov_b32_e32 v106, v2
	v_mov_b32_e32 v107, v2
	v_mov_b32_e32 v108, v2
	v_mov_b32_e32 v109, v2
	v_mov_b32_e32 v110, v2
	v_mov_b32_e32 v111, v2
	v_mov_b32_e32 v112, v2
	v_mov_b32_e32 v113, v2
	v_mov_b32_e32 v122, v2
	v_mov_b32_e32 v123, v2
	v_mov_b32_e32 v124, v2
	v_mov_b32_e32 v125, v2
	v_mov_b32_e32 v126, v2
	v_mov_b32_e32 v127, v2
	v_mov_b32_e32 v128, v2
	v_mov_b32_e32 v129, v2
	.p2align	6
.LBB0_920:
	s_add_u32 s8, s4, 0xfff80080
	s_addc_u32 s9, s5, -1
	s_add_i32 s46, 0, 0x10000
	s_cmp_eq_u32 s83, 28
	s_cselect_b32 s25, s17, s9
	s_cselect_b32 s24, s71, s8
	s_cselect_b32 s9, s15, s82
	s_cselect_b32 s8, s76, s77
	s_add_i32 s47, 0, 0x14000
	v_add_u32_e32 v154, s46, v161
	v_add_u32_e32 v158, s47, v161
	ds_read_b128 v[142:145], v154
	ds_read_b128 v[146:149], v154 offset:1024
	ds_read_b128 v[150:153], v154 offset:2048
	ds_read_b128 v[154:157], v154 offset:3072
	ds_read_b128 v[166:169], v158
	ds_read_b128 v[170:173], v158 offset:1024
	ds_read_b128 v[174:177], v158 offset:2048
	ds_read_b128 v[178:181], v158 offset:3072
	v_lshl_add_u64 v[158:159], s[4:5], 0, v[138:139]
	s_add_i32 m0, s31, 0xc000
	ds_read_b128 v[182:185], v163
	ds_read_b128 v[186:189], v163 offset:1024
	ds_read_b128 v[190:193], v163 offset:2048
	ds_read_b128 v[194:197], v163 offset:3072
	ds_read_b128 v[198:201], v163 offset:4096
	ds_read_b128 v[202:205], v163 offset:5120
	ds_read_b128 v[206:209], v163 offset:6144
	ds_read_b128 v[210:213], v163 offset:7168
	global_load_lds_dwordx4 v[158:159], off
	v_lshl_add_u64 v[158:159], s[4:5], 0, v[140:141]
	s_add_i32 m0, s31, 0xe000
	s_nop 0
	global_load_lds_dwordx4 v[158:159], off
	s_waitcnt vmcnt(8)
	s_waitcnt lgkmcnt(0)
	s_barrier
; #define PG8_STAGE(bufoff, gbase, voff) do { _Pragma("unroll") for (int _i = 0; _i < 2; ++_i) \
;         __builtin_amdgcn_global_load_lds((const unsigned*)((const char*)(gbase) + (voff)[_i]), (LAS unsigned*)(lds + (bufoff) + ldsw + _i * 8192), 16, 0, 0); } while (0)
; #define PG8_LDA(dst, b, h) do { _Pragma("unroll") for (int m = 0; m < 4; ++m) _Pragma("unroll") for (int k = 0; k < 2; ++k) dst[m][k] = *(const LAS bf16x8*)(lds + PG8_SA(b, h) + aoff + m * 2048 + k * 1024); } while (0)
; #define PG8_MMA(ai, bj, At, Bt) do { __builtin_amdgcn_s_setprio(1); _Pragma("unroll") for (int m = 0; m < 4; ++m) _Pragma("unroll") for (int n = 0; n < 2; ++n) _Pragma("unroll") for (int k = 0; k < 2; ++k) \
;         acc[ai][bj][m][n] = __builtin_amdgcn_mfma_f32_16x16x32_bf16(Bt[n][k], At[m][k], acc[ai][bj][m][n], 0, 0, 0); __builtin_amdgcn_s_setprio(0); } while (0)
; #define PG8_WAIT_V(n) asm volatile("s_waitcnt vmcnt(" #n ")" ::: "memory")
; #define PG8_WAIT_L(n) asm volatile("s_waitcnt lgkmcnt(" #n ")" ::: "memory")
; #define PG8_BAR __builtin_amdgcn_s_barrier()
; #define PG8_SCHED __builtin_amdgcn_sched_barrier(0)
; template <class Epi, class Sched>
; __device__ __forceinline__ void gemm_phase(LAS unsigned char* lds, const int K, const Sched& S, const Epi& E) {
;     ...
;             PG8_WAIT_V(8); PG8_WAIT_L(0); PG8_BAR; PG8_MMA(0, 0, At, B0); PG8_MMA(0, 1, At, B1); PG8_BAR; PG8_SCHED;
;             PG8_LDA(At, 0, 1); PG8_STAGE(PG8_SB(0, 0), b2, voffB); PG8_STAGE(PG8_SB(0, 1), b2 + hstep, voffB); PG8_STAGE(PG8_SA(0, 0), a2, voffA);
;             PG8_WAIT_V(8); PG8_WAIT_L(0); PG8_BAR; PG8_MMA(1, 0, At, B0); PG8_MMA(1, 1, At, B1); PG8_BAR; PG8_SCHED;
	s_setprio 1
	s_waitcnt lgkmcnt(0)
	v_mfma_f32_16x16x32_bf16 v[126:129], v[142:145], v[182:185], v[126:129]
	v_mfma_f32_16x16x32_bf16 v[122:125], v[150:153], v[182:185], v[122:125]
	v_mfma_f32_16x16x32_bf16 v[110:113], v[142:145], v[190:193], v[110:113]
	v_mfma_f32_16x16x32_bf16 v[106:109], v[150:153], v[190:193], v[106:109]
	v_mfma_f32_16x16x32_bf16 v[94:97], v[142:145], v[198:201], v[94:97]
	v_mfma_f32_16x16x32_bf16 v[90:93], v[150:153], v[198:201], v[90:93]
	v_mfma_f32_16x16x32_bf16 v[78:81], v[142:145], v[206:209], v[78:81]
	v_mfma_f32_16x16x32_bf16 v[74:77], v[150:153], v[206:209], v[74:77]
	v_mfma_f32_16x16x32_bf16 v[126:129], v[146:149], v[186:189], v[126:129]
	v_mfma_f32_16x16x32_bf16 v[122:125], v[154:157], v[186:189], v[122:125]
	v_mfma_f32_16x16x32_bf16 v[110:113], v[146:149], v[194:197], v[110:113]
	v_mfma_f32_16x16x32_bf16 v[106:109], v[154:157], v[194:197], v[106:109]
	v_mfma_f32_16x16x32_bf16 v[94:97], v[146:149], v[202:205], v[94:97]
	v_mfma_f32_16x16x32_bf16 v[90:93], v[154:157], v[202:205], v[90:93]
	v_mfma_f32_16x16x32_bf16 v[78:81], v[146:149], v[210:213], v[78:81]
	v_mfma_f32_16x16x32_bf16 v[74:77], v[154:157], v[210:213], v[74:77]
	s_setprio 0
	s_setprio 1
	v_mfma_f32_16x16x32_bf16 v[118:121], v[166:169], v[182:185], v[118:121]
	v_mfma_f32_16x16x32_bf16 v[114:117], v[174:177], v[182:185], v[114:117]
	v_mfma_f32_16x16x32_bf16 v[102:105], v[166:169], v[190:193], v[102:105]
	v_mfma_f32_16x16x32_bf16 v[98:101], v[174:177], v[190:193], v[98:101]
	v_mfma_f32_16x16x32_bf16 v[86:89], v[166:169], v[198:201], v[86:89]
	v_mfma_f32_16x16x32_bf16 v[82:85], v[174:177], v[198:201], v[82:85]
	v_mfma_f32_16x16x32_bf16 v[70:73], v[166:169], v[206:209], v[70:73]
	v_mfma_f32_16x16x32_bf16 v[66:69], v[174:177], v[206:209], v[66:69]
	v_mfma_f32_16x16x32_bf16 v[118:121], v[170:173], v[186:189], v[118:121]
	v_mfma_f32_16x16x32_bf16 v[114:117], v[178:181], v[186:189], v[114:117]
	v_mfma_f32_16x16x32_bf16 v[102:105], v[170:173], v[194:197], v[102:105]
	v_mfma_f32_16x16x32_bf16 v[98:101], v[178:181], v[194:197], v[98:101]
	v_mfma_f32_16x16x32_bf16 v[86:89], v[170:173], v[202:205], v[86:89]
	v_mfma_f32_16x16x32_bf16 v[82:85], v[178:181], v[202:205], v[82:85]
	v_mfma_f32_16x16x32_bf16 v[70:73], v[170:173], v[210:213], v[70:73]
	v_mfma_f32_16x16x32_bf16 v[66:69], v[178:181], v[210:213], v[66:69]
	s_setprio 0
	s_barrier
	s_add_i32 s46, s46, s30
	v_lshl_add_u64 v[158:159], s[8:9], 0, v[0:1]
	s_mov_b32 m0, s46
	ds_read_b128 v[182:185], v163 offset:16384
	ds_read_b128 v[186:189], v163 offset:17408
	ds_read_b128 v[190:193], v163 offset:18432
	ds_read_b128 v[194:197], v163 offset:19456
	ds_read_b128 v[198:201], v163 offset:20480
	ds_read_b128 v[202:205], v163 offset:21504
	ds_read_b128 v[206:209], v163 offset:22528
	ds_read_b128 v[210:213], v163 offset:23552
	global_load_lds_dwordx4 v[158:159], off
	s_add_i32 m0, s46, 0x2000
	s_add_u32 s86, s8, 0x80000
	v_lshl_add_u64 v[214:215], s[8:9], 0, v[130:131]
	s_addc_u32 s87, s9, 0
	s_add_i32 s46, s47, s30
	global_load_lds_dwordx4 v[214:215], off
	v_lshl_add_u64 v[216:217], s[86:87], 0, v[0:1]
	s_mov_b32 m0, s46
	v_lshl_add_u64 v[218:219], s[24:25], 0, v[132:133]
	global_load_lds_dwordx4 v[216:217], off
	v_lshl_add_u64 v[216:217], s[86:87], 0, v[130:131]
	s_add_i32 m0, s46, 0x2000
	s_nop 0
	global_load_lds_dwordx4 v[216:217], off
	v_lshl_add_u64 v[216:217], s[24:25], 0, v[134:135]
	s_mov_b32 m0, s31
	s_nop 0
	global_load_lds_dwordx4 v[216:217], off
	s_mov_b32 m0, s44
	s_nop 0
	global_load_lds_dwordx4 v[218:219], off
	s_waitcnt vmcnt(8)
	s_waitcnt lgkmcnt(0)
	s_barrier
	s_setprio 1
	s_waitcnt lgkmcnt(0)
	v_mfma_f32_16x16x32_bf16 v[62:65], v[142:145], v[182:185], v[62:65]
	v_mfma_f32_16x16x32_bf16 v[58:61], v[150:153], v[182:185], v[58:61]
	v_mfma_f32_16x16x32_bf16 v[46:49], v[142:145], v[190:193], v[46:49]
	v_mfma_f32_16x16x32_bf16 v[42:45], v[150:153], v[190:193], v[42:45]
	v_mfma_f32_16x16x32_bf16 v[30:33], v[142:145], v[198:201], v[30:33]
	v_mfma_f32_16x16x32_bf16 v[26:29], v[150:153], v[198:201], v[26:29]
	v_mfma_f32_16x16x32_bf16 v[14:17], v[142:145], v[206:209], v[14:17]
	v_mfma_f32_16x16x32_bf16 v[10:13], v[150:153], v[206:209], v[10:13]
	v_mfma_f32_16x16x32_bf16 v[62:65], v[146:149], v[186:189], v[62:65]
	v_mfma_f32_16x16x32_bf16 v[58:61], v[154:157], v[186:189], v[58:61]
	v_mfma_f32_16x16x32_bf16 v[46:49], v[146:149], v[194:197], v[46:49]
	v_mfma_f32_16x16x32_bf16 v[42:45], v[154:157], v[194:197], v[42:45]
	v_mfma_f32_16x16x32_bf16 v[30:33], v[146:149], v[202:205], v[30:33]
	v_mfma_f32_16x16x32_bf16 v[26:29], v[154:157], v[202:205], v[26:29]
	v_mfma_f32_16x16x32_bf16 v[14:17], v[146:149], v[210:213], v[14:17]
	v_mfma_f32_16x16x32_bf16 v[10:13], v[154:157], v[210:213], v[10:13]
	s_setprio 0
	s_setprio 1
	v_mfma_f32_16x16x32_bf16 v[54:57], v[166:169], v[182:185], v[54:57]
	v_mfma_f32_16x16x32_bf16 v[50:53], v[174:177], v[182:185], v[50:53]
	v_mfma_f32_16x16x32_bf16 v[38:41], v[166:169], v[190:193], v[38:41]
	v_mfma_f32_16x16x32_bf16 v[34:37], v[174:177], v[190:193], v[34:37]
	v_mfma_f32_16x16x32_bf16 v[22:25], v[166:169], v[198:201], v[22:25]
	v_mfma_f32_16x16x32_bf16 v[18:21], v[174:177], v[198:201], v[18:21]
	v_mfma_f32_16x16x32_bf16 v[6:9], v[166:169], v[206:209], v[6:9]
	v_mfma_f32_16x16x32_bf16 v[2:5], v[174:177], v[206:209], v[2:5]
	v_mfma_f32_16x16x32_bf16 v[54:57], v[170:173], v[186:189], v[54:57]
	v_mfma_f32_16x16x32_bf16 v[50:53], v[178:181], v[186:189], v[50:53]
	v_mfma_f32_16x16x32_bf16 v[38:41], v[170:173], v[194:197], v[38:41]
	v_mfma_f32_16x16x32_bf16 v[34:37], v[178:181], v[194:197], v[34:37]
	v_mfma_f32_16x16x32_bf16 v[22:25], v[170:173], v[202:205], v[22:25]
	v_mfma_f32_16x16x32_bf16 v[18:21], v[178:181], v[202:205], v[18:21]
	v_mfma_f32_16x16x32_bf16 v[6:9], v[170:173], v[210:213], v[6:9]
	v_mfma_f32_16x16x32_bf16 v[2:5], v[178:181], v[210:213], v[2:5]
	s_setprio 0
	s_barrier
; #define PG8_STAGE(bufoff, gbase, voff) do { _Pragma("unroll") for (int _i = 0; _i < 2; ++_i) \
;         __builtin_amdgcn_global_load_lds((const unsigned*)((const char*)(gbase) + (voff)[_i]), (LAS unsigned*)(lds + (bufoff) + ldsw + _i * 8192), 16, 0, 0); } while (0)
; #define PG8_LDA(dst, b, h) do { _Pragma("unroll") for (int m = 0; m < 4; ++m) _Pragma("unroll") for (int k = 0; k < 2; ++k) dst[m][k] = *(const LAS bf16x8*)(lds + PG8_SA(b, h) + aoff + m * 2048 + k * 1024); } while (0)
; #define PG8_LDB(dst, b, h) do { _Pragma("unroll") for (int n = 0; n < 2; ++n) _Pragma("unroll") for (int k = 0; k < 2; ++k) dst[n][k] = *(const LAS bf16x8*)(lds + PG8_SB(b, h) + boff + n * 2048 + k * 1024); } while (0)
; #define PG8_MMA(ai, bj, At, Bt) do { __builtin_amdgcn_s_setprio(1); _Pragma("unroll") for (int m = 0; m < 4; ++m) _Pragma("unroll") for (int n = 0; n < 2; ++n) _Pragma("unroll") for (int k = 0; k < 2; ++k) \
;         acc[ai][bj][m][n] = __builtin_amdgcn_mfma_f32_16x16x32_bf16(Bt[n][k], At[m][k], acc[ai][bj][m][n], 0, 0, 0); __builtin_amdgcn_s_setprio(0); } while (0)
; #define PG8_WAIT_V(n) asm volatile("s_waitcnt vmcnt(" #n ")" ::: "memory")
; #define PG8_WAIT_L(n) asm volatile("s_waitcnt lgkmcnt(" #n ")" ::: "memory")
; #define PG8_BAR __builtin_amdgcn_s_barrier()
; #define PG8_SCHED __builtin_amdgcn_sched_barrier(0)
; template <class Epi, class Sched>
; __device__ __forceinline__ void gemm_phase(LAS unsigned char* lds, const int K, const Sched& S, const Epi& E) {
;     ...
;             PG8_LDB(B0, 1, 0); PG8_LDB(B1, 1, 1); PG8_SCHED; PG8_LDA(At, 1, 0); PG8_STAGE(PG8_SA(0, 1), a2 + hstep, voffA);
;             PG8_WAIT_V(8); PG8_WAIT_L(0); PG8_BAR; PG8_MMA(0, 0, At, B0); PG8_MMA(0, 1, At, B1); PG8_BAR; PG8_SCHED;
	s_add_i32 s46, 0, 0x18000
	s_add_i32 s47, 0, 0x1c000
	v_add_u32_e32 v154, s46, v161
	v_add_u32_e32 v165, s47, v161
	ds_read_b128 v[142:145], v154
	ds_read_b128 v[146:149], v154 offset:1024
	ds_read_b128 v[150:153], v154 offset:2048
	ds_read_b128 v[154:157], v154 offset:3072
	ds_read_b128 v[166:169], v165
	ds_read_b128 v[170:173], v165 offset:1024
	ds_read_b128 v[174:177], v165 offset:2048
	ds_read_b128 v[178:181], v165 offset:3072
	s_add_u32 s24, s24, 0x80000
	s_addc_u32 s25, s25, 0
	s_mov_b32 m0, s54
	v_lshl_add_u64 v[220:221], s[24:25], 0, v[134:135]
	ds_read_b128 v[182:185], v163 offset:32768
	ds_read_b128 v[186:189], v163 offset:33792
	ds_read_b128 v[190:193], v163 offset:34816
	ds_read_b128 v[194:197], v163 offset:35840
	ds_read_b128 v[198:201], v163 offset:36864
	ds_read_b128 v[202:205], v163 offset:37888
	ds_read_b128 v[206:209], v163 offset:38912
	ds_read_b128 v[210:213], v163 offset:39936
	global_load_lds_dwordx4 v[220:221], off
	v_lshl_add_u64 v[220:221], s[24:25], 0, v[132:133]
	s_mov_b32 m0, s55
	s_nop 0
	global_load_lds_dwordx4 v[220:221], off
	s_waitcnt vmcnt(8)
	s_waitcnt lgkmcnt(0)
	s_barrier
	s_setprio 1
	s_waitcnt lgkmcnt(0)
	v_mfma_f32_16x16x32_bf16 v[126:129], v[142:145], v[182:185], v[126:129]
	v_mfma_f32_16x16x32_bf16 v[122:125], v[150:153], v[182:185], v[122:125]
	v_mfma_f32_16x16x32_bf16 v[110:113], v[142:145], v[190:193], v[110:113]
	v_mfma_f32_16x16x32_bf16 v[106:109], v[150:153], v[190:193], v[106:109]
	v_mfma_f32_16x16x32_bf16 v[94:97], v[142:145], v[198:201], v[94:97]
	v_mfma_f32_16x16x32_bf16 v[90:93], v[150:153], v[198:201], v[90:93]
	v_mfma_f32_16x16x32_bf16 v[78:81], v[142:145], v[206:209], v[78:81]
	v_mfma_f32_16x16x32_bf16 v[74:77], v[150:153], v[206:209], v[74:77]
	v_mfma_f32_16x16x32_bf16 v[126:129], v[146:149], v[186:189], v[126:129]
	v_mfma_f32_16x16x32_bf16 v[122:125], v[154:157], v[186:189], v[122:125]
	v_mfma_f32_16x16x32_bf16 v[110:113], v[146:149], v[194:197], v[110:113]
	v_mfma_f32_16x16x32_bf16 v[106:109], v[154:157], v[194:197], v[106:109]
	v_mfma_f32_16x16x32_bf16 v[94:97], v[146:149], v[202:205], v[94:97]
	v_mfma_f32_16x16x32_bf16 v[90:93], v[154:157], v[202:205], v[90:93]
	v_mfma_f32_16x16x32_bf16 v[78:81], v[146:149], v[210:213], v[78:81]
	v_mfma_f32_16x16x32_bf16 v[74:77], v[154:157], v[210:213], v[74:77]
	s_setprio 0
	s_setprio 1
	v_mfma_f32_16x16x32_bf16 v[118:121], v[166:169], v[182:185], v[118:121]
	v_mfma_f32_16x16x32_bf16 v[114:117], v[174:177], v[182:185], v[114:117]
	v_mfma_f32_16x16x32_bf16 v[102:105], v[166:169], v[190:193], v[102:105]
	v_mfma_f32_16x16x32_bf16 v[98:101], v[174:177], v[190:193], v[98:101]
	v_mfma_f32_16x16x32_bf16 v[86:89], v[166:169], v[198:201], v[86:89]
	v_mfma_f32_16x16x32_bf16 v[82:85], v[174:177], v[198:201], v[82:85]
	v_mfma_f32_16x16x32_bf16 v[70:73], v[166:169], v[206:209], v[70:73]
	v_mfma_f32_16x16x32_bf16 v[66:69], v[174:177], v[206:209], v[66:69]
	v_mfma_f32_16x16x32_bf16 v[118:121], v[170:173], v[186:189], v[118:121]
	v_mfma_f32_16x16x32_bf16 v[114:117], v[178:181], v[186:189], v[114:117]
	v_mfma_f32_16x16x32_bf16 v[102:105], v[170:173], v[194:197], v[102:105]
	v_mfma_f32_16x16x32_bf16 v[98:101], v[178:181], v[194:197], v[98:101]
	v_mfma_f32_16x16x32_bf16 v[86:89], v[170:173], v[202:205], v[86:89]
	v_mfma_f32_16x16x32_bf16 v[82:85], v[178:181], v[202:205], v[82:85]
	v_mfma_f32_16x16x32_bf16 v[70:73], v[170:173], v[210:213], v[70:73]
	v_mfma_f32_16x16x32_bf16 v[66:69], v[178:181], v[210:213], v[66:69]
	s_setprio 0
	s_barrier
; #define PG8_STAGE(bufoff, gbase, voff) do { _Pragma("unroll") for (int _i = 0; _i < 2; ++_i) \
;         __builtin_amdgcn_global_load_lds((const unsigned*)((const char*)(gbase) + (voff)[_i]), (LAS unsigned*)(lds + (bufoff) + ldsw + _i * 8192), 16, 0, 0); } while (0)
; #define PG8_LDA(dst, b, h) do { _Pragma("unroll") for (int m = 0; m < 4; ++m) _Pragma("unroll") for (int k = 0; k < 2; ++k) dst[m][k] = *(const LAS bf16x8*)(lds + PG8_SA(b, h) + aoff + m * 2048 + k * 1024); } while (0)
; #define PG8_MMA(ai, bj, At, Bt) do { __builtin_amdgcn_s_setprio(1); _Pragma("unroll") for (int m = 0; m < 4; ++m) _Pragma("unroll") for (int n = 0; n < 2; ++n) _Pragma("unroll") for (int k = 0; k < 2; ++k) \
;         acc[ai][bj][m][n] = __builtin_amdgcn_mfma_f32_16x16x32_bf16(Bt[n][k], At[m][k], acc[ai][bj][m][n], 0, 0, 0); __builtin_amdgcn_s_setprio(0); } while (0)
; #define PG8_WAIT_V(n) asm volatile("s_waitcnt vmcnt(" #n ")" ::: "memory")
; #define PG8_WAIT_L(n) asm volatile("s_waitcnt lgkmcnt(" #n ")" ::: "memory")
; #define PG8_BAR __builtin_amdgcn_s_barrier()
; #define PG8_SCHED __builtin_amdgcn_sched_barrier(0)
; template <class Epi, class Sched>
; __device__ __forceinline__ void gemm_phase(LAS unsigned char* lds, const int K, const Sched& S, const Epi& E) {
;     ...
;             PG8_LDA(At, 1, 1); PG8_STAGE(PG8_SB(1, 0), b3, voffB); PG8_STAGE(PG8_SB(1, 1), b3 + hstep, voffB); PG8_STAGE(PG8_SA(1, 0), a3, voffA);
;             PG8_WAIT_V(8); PG8_WAIT_L(0); PG8_BAR; PG8_MMA(1, 0, At, B0); PG8_MMA(1, 1, At, B1); PG8_BAR; PG8_SCHED;
;         }
;         if (wr == 0) PG8_BAR;
	s_add_i32 s24, s46, s30
	v_lshl_add_u64 v[158:159], v[158:159], 0, s[52:53]
	s_mov_b32 m0, s24
	ds_read_b128 v[182:185], v163 offset:49152
	ds_read_b128 v[186:189], v163 offset:50176
	ds_read_b128 v[190:193], v163 offset:51200
	ds_read_b128 v[194:197], v163 offset:52224
	ds_read_b128 v[198:201], v163 offset:53248
	ds_read_b128 v[202:205], v163 offset:54272
	ds_read_b128 v[206:209], v163 offset:55296
	ds_read_b128 v[210:213], v163 offset:56320
	global_load_lds_dwordx4 v[158:159], off
	s_add_i32 m0, s24, 0x2000
	s_add_u32 s8, s8, 0x80080
	v_lshl_add_u64 v[158:159], v[214:215], 0, s[52:53]
	s_addc_u32 s9, s9, 0
	s_add_i32 s24, s47, s30
	global_load_lds_dwordx4 v[158:159], off
	v_lshl_add_u64 v[158:159], s[8:9], 0, v[0:1]
	s_mov_b32 m0, s24
	s_nop 0
	global_load_lds_dwordx4 v[158:159], off
	v_lshl_add_u64 v[158:159], s[8:9], 0, v[130:131]
	s_add_i32 m0, s24, 0x2000
	s_nop 0
	global_load_lds_dwordx4 v[158:159], off
	v_lshl_add_u64 v[158:159], v[216:217], 0, s[52:53]
	s_mov_b32 m0, s59
	s_nop 0
	global_load_lds_dwordx4 v[158:159], off
	v_lshl_add_u64 v[158:159], v[218:219], 0, s[52:53]
	s_mov_b32 m0, s60
	s_nop 0
	global_load_lds_dwordx4 v[158:159], off
	s_waitcnt vmcnt(8)
	s_waitcnt lgkmcnt(0)
	s_barrier
	s_setprio 1
	s_waitcnt lgkmcnt(0)
	v_mfma_f32_16x16x32_bf16 v[62:65], v[142:145], v[182:185], v[62:65]
	v_mfma_f32_16x16x32_bf16 v[58:61], v[150:153], v[182:185], v[58:61]
	v_mfma_f32_16x16x32_bf16 v[46:49], v[142:145], v[190:193], v[46:49]
	v_mfma_f32_16x16x32_bf16 v[42:45], v[150:153], v[190:193], v[42:45]
	v_mfma_f32_16x16x32_bf16 v[30:33], v[142:145], v[198:201], v[30:33]
	v_mfma_f32_16x16x32_bf16 v[26:29], v[150:153], v[198:201], v[26:29]
	v_mfma_f32_16x16x32_bf16 v[14:17], v[142:145], v[206:209], v[14:17]
	v_mfma_f32_16x16x32_bf16 v[10:13], v[150:153], v[206:209], v[10:13]
	v_mfma_f32_16x16x32_bf16 v[62:65], v[146:149], v[186:189], v[62:65]
	v_mfma_f32_16x16x32_bf16 v[58:61], v[154:157], v[186:189], v[58:61]
	v_mfma_f32_16x16x32_bf16 v[46:49], v[146:149], v[194:197], v[46:49]
	v_mfma_f32_16x16x32_bf16 v[42:45], v[154:157], v[194:197], v[42:45]
	v_mfma_f32_16x16x32_bf16 v[30:33], v[146:149], v[202:205], v[30:33]
	v_mfma_f32_16x16x32_bf16 v[26:29], v[154:157], v[202:205], v[26:29]
	v_mfma_f32_16x16x32_bf16 v[14:17], v[146:149], v[210:213], v[14:17]
	v_mfma_f32_16x16x32_bf16 v[10:13], v[154:157], v[210:213], v[10:13]
	s_setprio 0
	s_setprio 1
	v_mfma_f32_16x16x32_bf16 v[54:57], v[166:169], v[182:185], v[54:57]
	v_mfma_f32_16x16x32_bf16 v[50:53], v[174:177], v[182:185], v[50:53]
	v_mfma_f32_16x16x32_bf16 v[38:41], v[166:169], v[190:193], v[38:41]
	v_mfma_f32_16x16x32_bf16 v[34:37], v[174:177], v[190:193], v[34:37]
	v_mfma_f32_16x16x32_bf16 v[22:25], v[166:169], v[198:201], v[22:25]
	v_mfma_f32_16x16x32_bf16 v[18:21], v[174:177], v[198:201], v[18:21]
	v_mfma_f32_16x16x32_bf16 v[6:9], v[166:169], v[206:209], v[6:9]
	v_mfma_f32_16x16x32_bf16 v[2:5], v[174:177], v[206:209], v[2:5]
	v_mfma_f32_16x16x32_bf16 v[54:57], v[170:173], v[186:189], v[54:57]
	v_mfma_f32_16x16x32_bf16 v[50:53], v[178:181], v[186:189], v[50:53]
	v_mfma_f32_16x16x32_bf16 v[38:41], v[170:173], v[194:197], v[38:41]
	v_mfma_f32_16x16x32_bf16 v[34:37], v[178:181], v[194:197], v[34:37]
	v_mfma_f32_16x16x32_bf16 v[22:25], v[170:173], v[202:205], v[22:25]
	v_mfma_f32_16x16x32_bf16 v[18:21], v[178:181], v[202:205], v[18:21]
	v_mfma_f32_16x16x32_bf16 v[6:9], v[170:173], v[210:213], v[6:9]
	v_mfma_f32_16x16x32_bf16 v[2:5], v[178:181], v[210:213], v[2:5]
	s_setprio 0
	s_barrier
	s_add_i32 s83, s83, 2
	s_add_u32 s4, s4, 0x100
	s_addc_u32 s5, s5, 0
	s_add_u32 s77, s77, 0x100
	s_addc_u32 s82, s82, 0
	s_cmp_gt_u32 s83, 29
	s_cbranch_scc0 .LBB0_920
	s_and_b64 vcc, exec, s[12:13]
	s_cbranch_vccz .LBB0_923
	s_barrier
